# v046 combo + batched residual loads in mix-out/xattn-out epilogue (counted vmcnt)
# speedup vs baseline: 1.0141x; 1.0141x over previous
.Lkx_246:
	s_mov_b32 s2, 0x18000
	v_add3_u32 v144, v134, v135, s2
	v_add3_u32 v135, v132, v135, s81
	ds_read_b128 v[128:131], v144
	ds_read_b128 v[136:139], v144 offset:2048
	ds_read_b128 v[140:143], v144 offset:4096
	ds_read_b128 v[146:149], v144 offset:6144
	ds_read_b128 v[154:157], v135
	ds_read_b128 v[158:161], v135 offset:2048
	ds_read_b128 v[162:165], v135 offset:4096
	ds_read_b128 v[166:169], v135 offset:6144
	ds_read_b128 v[170:173], v135 offset:8192
	ds_read_b128 v[174:177], v135 offset:10240
	ds_read_b128 v[178:181], v135 offset:12288
	ds_read_b128 v[182:185], v135 offset:14336
	s_waitcnt lgkmcnt(7)
	v_mfma_f32_16x16x32_bf16 v[120:123], v[136:139], v[154:157], v[120:123]
	v_mfma_f32_16x16x32_bf16 v[116:119], v[140:143], v[154:157], v[116:119]
	v_mfma_f32_16x16x32_bf16 v[112:115], v[146:149], v[154:157], v[112:115]
	s_waitcnt lgkmcnt(6)
	v_mfma_f32_16x16x32_bf16 v[108:111], v[128:131], v[158:161], v[108:111]
	v_mfma_f32_16x16x32_bf16 v[104:107], v[136:139], v[158:161], v[104:107]
	v_mfma_f32_16x16x32_bf16 v[100:103], v[140:143], v[158:161], v[100:103]
	v_mfma_f32_16x16x32_bf16 v[96:99], v[146:149], v[158:161], v[96:99]
	s_waitcnt lgkmcnt(5)
	v_mfma_f32_16x16x32_bf16 v[92:95], v[128:131], v[162:165], v[92:95]
	v_mfma_f32_16x16x32_bf16 v[84:87], v[136:139], v[162:165], v[84:87]
	v_mfma_f32_16x16x32_bf16 v[80:83], v[140:143], v[162:165], v[80:83]
	v_mfma_f32_16x16x32_bf16 v[76:79], v[146:149], v[162:165], v[76:79]
	s_waitcnt lgkmcnt(4)
	v_mfma_f32_16x16x32_bf16 v[72:75], v[128:131], v[166:169], v[72:75]
	v_mfma_f32_16x16x32_bf16 v[68:71], v[136:139], v[166:169], v[68:71]
	v_mfma_f32_16x16x32_bf16 v[64:67], v[140:143], v[166:169], v[64:67]
	v_mfma_f32_16x16x32_bf16 v[60:63], v[146:149], v[166:169], v[60:63]
	v_mfma_f32_16x16x32_bf16 v[124:127], v[128:131], v[154:157], v[124:127]
	v_add3_u32 v134, v134, v133, s2
	v_add3_u32 v144, v132, v133, s81
	ds_read_b128 v[154:157], v134
	ds_read_b128 v[158:161], v134 offset:2048
	ds_read_b128 v[162:165], v134 offset:4096
	ds_read_b128 v[166:169], v134 offset:6144
	ds_read_b128 v[132:135], v144
	ds_read_b128 v[186:189], v144 offset:2048
	ds_read_b128 v[206:209], v144 offset:4096
	ds_read_b128 v[216:219], v144 offset:6144
	s_waitcnt lgkmcnt(11)
	v_mfma_f32_16x16x32_bf16 v[56:59], v[128:131], v[170:173], v[56:59]
	v_mfma_f32_16x16x32_bf16 v[52:55], v[136:139], v[170:173], v[52:55]
	v_mfma_f32_16x16x32_bf16 v[48:51], v[140:143], v[170:173], v[48:51]
	v_mfma_f32_16x16x32_bf16 v[44:47], v[146:149], v[170:173], v[44:47]
	s_waitcnt lgkmcnt(10)
	v_mfma_f32_16x16x32_bf16 v[40:43], v[128:131], v[174:177], v[40:43]
	v_mfma_f32_16x16x32_bf16 v[36:39], v[136:139], v[174:177], v[36:39]
	v_mfma_f32_16x16x32_bf16 v[32:35], v[140:143], v[174:177], v[32:35]
	v_mfma_f32_16x16x32_bf16 v[28:31], v[146:149], v[174:177], v[28:31]
	s_waitcnt lgkmcnt(9)
	v_mfma_f32_16x16x32_bf16 v[24:27], v[128:131], v[178:181], v[24:27]
	v_mfma_f32_16x16x32_bf16 v[20:23], v[136:139], v[178:181], v[20:23]
	v_mfma_f32_16x16x32_bf16 v[16:19], v[140:143], v[178:181], v[16:19]
	v_mfma_f32_16x16x32_bf16 v[12:15], v[146:149], v[178:181], v[12:15]
	s_waitcnt lgkmcnt(8)
	v_mfma_f32_16x16x32_bf16 v[8:11], v[128:131], v[182:185], v[8:11]
	v_mfma_f32_16x16x32_bf16 v[4:7], v[136:139], v[182:185], v[4:7]
	v_mfma_f32_16x16x32_bf16 v[0:3], v[140:143], v[182:185], v[0:3]
	v_mfma_f32_16x16x32_bf16 v[128:131], v[146:149], v[182:185], v[88:91]
	ds_read_b128 v[136:139], v144 offset:8192
	ds_read_b128 v[140:143], v144 offset:10240
	ds_read_b128 v[146:149], v144 offset:12288
	ds_read_b128 v[170:173], v144 offset:14336
	s_waitcnt lgkmcnt(7)
	v_mfma_f32_16x16x32_bf16 v[120:123], v[158:161], v[132:135], v[120:123]
	s_waitcnt lgkmcnt(6)
	v_mfma_f32_16x16x32_bf16 v[108:111], v[154:157], v[186:189], v[108:111]
	v_mfma_f32_16x16x32_bf16 v[104:107], v[158:161], v[186:189], v[104:107]
	v_mfma_f32_16x16x32_bf16 v[100:103], v[162:165], v[186:189], v[100:103]
	v_mfma_f32_16x16x32_bf16 v[96:99], v[166:169], v[186:189], v[96:99]
	s_waitcnt lgkmcnt(5)
	v_mfma_f32_16x16x32_bf16 v[92:95], v[154:157], v[206:209], v[92:95]
	v_mfma_f32_16x16x32_bf16 v[88:91], v[158:161], v[206:209], v[84:87]
	v_mfma_f32_16x16x32_bf16 v[84:87], v[162:165], v[206:209], v[80:83]
	v_mfma_f32_16x16x32_bf16 v[80:83], v[166:169], v[206:209], v[76:79]
	s_waitcnt lgkmcnt(4)
	v_mfma_f32_16x16x32_bf16 v[76:79], v[154:157], v[216:219], v[72:75]
	v_mfma_f32_16x16x32_bf16 v[72:75], v[158:161], v[216:219], v[68:71]
	v_mfma_f32_16x16x32_bf16 v[68:71], v[162:165], v[216:219], v[64:67]
	v_mfma_f32_16x16x32_bf16 v[64:67], v[166:169], v[216:219], v[60:63]
	v_mfma_f32_16x16x32_bf16 v[124:127], v[154:157], v[132:135], v[124:127]
	v_mfma_f32_16x16x32_bf16 v[174:177], v[162:165], v[132:135], v[116:119]
	v_mfma_f32_16x16x32_bf16 v[132:135], v[166:169], v[132:135], v[112:115]
	s_nop 2
	v_mov_b32_e32 v112, v190
	s_lshl_b32 s2, s22, 8
	s_waitcnt lgkmcnt(3)
	v_mfma_f32_16x16x32_bf16 v[60:63], v[154:157], v[136:139], v[56:59]
	v_ashrrev_i32_e32 v113, 1, v112
	s_lshl_b32 s3, s18, 8
	v_bfe_u32 v144, v112, 6, 2
	v_mfma_f32_16x16x32_bf16 v[56:59], v[158:161], v[136:139], v[52:55]
	v_bfe_u32 v151, v112, 4, 2
	v_mfma_f32_16x16x32_bf16 v[52:55], v[162:165], v[136:139], v[48:51]
	v_mfma_f32_16x16x32_bf16 v[48:51], v[166:169], v[136:139], v[44:47]
	s_waitcnt lgkmcnt(2)
	v_mfma_f32_16x16x32_bf16 v[44:47], v[154:157], v[140:143], v[40:43]
	v_mfma_f32_16x16x32_bf16 v[40:43], v[158:161], v[140:143], v[36:39]
	v_mfma_f32_16x16x32_bf16 v[36:39], v[162:165], v[140:143], v[32:35]
	v_mfma_f32_16x16x32_bf16 v[32:35], v[166:169], v[140:143], v[28:31]
	s_nop 2
	v_and_b32_e32 v28, 0xffffff80, v113
	v_and_or_b32 v29, v112, 15, s2
	v_add_u32_e32 v114, v29, v28
	s_ashr_i32 s2, s3, 31
	v_lshlrev_b32_e32 v112, 6, v144
	v_lshlrev_b32_e32 v113, 2, v151
	v_ashrrev_i32_e32 v115, 31, v114
	s_waitcnt lgkmcnt(1)
	v_mfma_f32_16x16x32_bf16 v[28:31], v[154:157], v[146:149], v[24:27]
	v_or3_b32 v116, s3, v112, v113
	v_mov_b32_e32 v117, s2
	v_mfma_f32_16x16x32_bf16 v[24:27], v[158:161], v[146:149], v[20:23]
	v_mfma_f32_16x16x32_bf16 v[20:23], v[162:165], v[146:149], v[16:19]
	s_nop 2
	v_lshlrev_b64 v[16:17], 10, v[114:115]
	v_lshl_add_u64 v[112:113], v[116:117], 0, v[16:17]
	v_lshl_add_u64 v[178:179], v[112:113], 2, s[90:91]
	global_load_dwordx4 v[228:231], v[178:179], off
	global_load_dwordx4 v[232:235], v[178:179], off offset:64
	global_load_dwordx4 v[236:239], v[178:179], off offset:128
	global_load_dwordx4 v[240:243], v[178:179], off offset:192
	v_lshlrev_b64 v[112:113], 1, v[112:113]
	v_mfma_f32_16x16x32_bf16 v[16:19], v[166:169], v[146:149], v[12:15]
	s_waitcnt vmcnt(3)
	v_pk_add_f32 v[126:127], v[126:127], v[230:231]
	s_waitcnt lgkmcnt(0)
	v_mfma_f32_16x16x32_bf16 v[12:15], v[154:157], v[170:173], v[8:11]
	v_add_f32_e64 v124, v124, v228
	v_add_f32_e64 v125, v125, v229
	global_store_dwordx4 v[178:179], v[124:127], off
	v_cvt_pk_bf16_f32 v10, v124, v125
	v_cvt_pk_bf16_f32 v11, v126, v127
	v_lshl_add_u64 v[8:9], s[16:17], 0, v[112:113]
	flat_store_dwordx2 v[8:9], v[10:11]
	v_mfma_f32_16x16x32_bf16 v[8:11], v[158:161], v[170:173], v[4:7]
	s_waitcnt vmcnt(4)
	v_pk_add_f32 v[138:139], v[122:123], v[234:235]
	s_nop 0
	v_or_b32_e32 v4, 32, v112
	v_mov_b32_e32 v5, v113
	v_lshl_add_u64 v[4:5], s[16:17], 0, v[4:5]
	v_pk_add_f32 v[136:137], v[120:121], v[232:233]
	global_store_dwordx4 v[178:179], v[136:139], off offset:64
	v_cvt_pk_bf16_f32 v6, v136, v137
	v_cvt_pk_bf16_f32 v7, v138, v139
	flat_store_dwordx2 v[4:5], v[6:7]
	v_mfma_f32_16x16x32_bf16 v[4:7], v[162:165], v[170:173], v[0:3]
	v_mul_f32_e32 v122, v137, v137
	v_fmac_f32_e32 v122, v136, v136
	v_fmac_f32_e32 v122, v138, v138
	v_or_b32_e32 v0, 64, v112
	v_mov_b32_e32 v1, v113
	v_lshl_add_u64 v[0:1], s[16:17], 0, v[0:1]
	v_fmac_f32_e32 v122, v139, v139
	v_or_b32_e32 v112, 0x60, v112
	v_lshl_add_u64 v[112:113], s[16:17], 0, v[112:113]
	s_waitcnt vmcnt(5)
	v_pk_add_f32 v[142:143], v[176:177], v[238:239]
	v_pk_add_f32 v[140:141], v[174:175], v[236:237]
	global_store_dwordx4 v[178:179], v[140:143], off offset:128
	v_cvt_pk_bf16_f32 v2, v140, v141
	v_cvt_pk_bf16_f32 v3, v142, v143
	flat_store_dwordx2 v[0:1], v[2:3]
	v_and_b32_e32 v119, 64, v194
	v_xor_b32_e32 v118, 16, v194
	v_add_u32_e32 v119, 64, v119
	v_xor_b32_e32 v120, 32, v194
	v_cmp_lt_i32_e32 vcc, v118, v119
	v_mfma_f32_16x16x32_bf16 v[0:3], v[166:169], v[170:173], v[128:131]
	s_nop 0
	v_cndmask_b32_e32 v121, v194, v118, vcc
	v_cmp_lt_i32_e32 vcc, v120, v119
	v_lshl_or_b32 v118, s18, 2, v144
	v_ashrrev_i32_e32 v119, 31, v118
	v_cndmask_b32_e32 v128, v194, v120, vcc
	v_lshlrev_b32_e32 v120, 2, v121
	v_mul_f32_e32 v121, v125, v125
	v_fmac_f32_e32 v121, v124, v124
	v_fmac_f32_e32 v121, v126, v126
	v_fmac_f32_e32 v121, v127, v127
	v_add_f32_e32 v121, v121, v122
	v_mul_f32_e32 v122, v141, v141
	v_fmac_f32_e32 v122, v140, v140
	v_fmac_f32_e32 v122, v142, v142
	v_fmac_f32_e32 v122, v143, v143
	v_add_f32_e32 v121, v121, v122
	v_lshlrev_b64 v[118:119], 16, v[118:119]
	v_cmp_eq_u32_e32 vcc, 0, v151
	s_waitcnt vmcnt(6)
	v_pk_add_f32 v[122:123], v[132:133], v[240:241]
	s_nop 0
	v_mul_f32_e32 v126, v123, v123
	v_pk_add_f32 v[124:125], v[134:135], v[242:243]
	v_fmac_f32_e32 v126, v122, v122
	v_fmac_f32_e32 v126, v124, v124
	v_fmac_f32_e32 v126, v125, v125
	v_add_f32_e32 v121, v121, v126
	ds_bpermute_b32 v129, v120, v121
	v_lshl_add_u64 v[126:127], s[8:9], 0, v[118:119]
	global_store_dwordx4 v[178:179], v[122:125], off offset:192
	s_waitcnt lgkmcnt(0)
	v_add_f32_e32 v118, v121, v129
	v_lshlrev_b32_e32 v121, 2, v128
	ds_bpermute_b32 v119, v121, v118
	v_cvt_pk_bf16_f32 v122, v122, v123
	v_cvt_pk_bf16_f32 v123, v124, v125
	flat_store_dwordx2 v[112:113], v[122:123]
	v_lshl_add_u64 v[112:113], v[114:115], 2, v[126:127]
	s_and_saveexec_b64 s[2:3], vcc
	s_cbranch_execz .LBB0_249
	s_waitcnt lgkmcnt(0)
	v_add_f32_e32 v115, v118, v119
	flat_store_dword v[112:113], v115
.LBB0_249:
	s_or_b64 exec, exec, s[2:3]
	v_or_b32_e32 v118, 16, v114
	s_waitcnt lgkmcnt(0)
	v_ashrrev_i32_e32 v119, 31, v118
	v_lshlrev_b64 v[118:119], 10, v[118:119]
	v_lshl_add_u64 v[126:127], v[116:117], 0, v[118:119]
	v_lshl_add_u64 v[118:119], v[126:127], 2, s[90:91]
	global_load_dwordx4 v[228:231], v[118:119], off
	global_load_dwordx4 v[232:235], v[118:119], off offset:64
	global_load_dwordx4 v[236:239], v[118:119], off offset:128
	global_load_dwordx4 v[240:243], v[118:119], off offset:192
	s_waitcnt vmcnt(3)
	v_pk_add_f32 v[108:109], v[108:109], v[228:229]
	v_pk_add_f32 v[110:111], v[110:111], v[230:231]
	v_lshlrev_b64 v[124:125], 1, v[126:127]
	v_mul_f32_e32 v115, v109, v109
	v_lshl_add_u64 v[126:127], s[16:17], 0, v[124:125]
	v_fmac_f32_e32 v115, v108, v108
	global_store_dwordx4 v[118:119], v[108:111], off
	v_cvt_pk_bf16_f32 v122, v108, v109
	v_cvt_pk_bf16_f32 v123, v110, v111
	flat_store_dwordx2 v[126:127], v[122:123]
	v_fmac_f32_e32 v115, v110, v110
	v_fmac_f32_e32 v115, v111, v111
	s_waitcnt vmcnt(4)
	v_pk_add_f32 v[106:107], v[106:107], v[234:235]
	v_pk_add_f32 v[104:105], v[104:105], v[232:233]
	global_store_dwordx4 v[118:119], v[104:107], off offset:64
	v_cvt_pk_bf16_f32 v108, v104, v105
	v_or_b32_e32 v110, 32, v124
	v_mov_b32_e32 v111, v125
	v_mul_f32_e32 v105, v105, v105
	v_fmac_f32_e32 v105, v104, v104
	v_lshl_add_u64 v[110:111], s[16:17], 0, v[110:111]
	v_fmac_f32_e32 v105, v106, v106
	v_cvt_pk_bf16_f32 v109, v106, v107
	flat_store_dwordx2 v[110:111], v[108:109]
	v_fmac_f32_e32 v105, v107, v107
	v_add_f32_e32 v108, v115, v105
	s_waitcnt vmcnt(5)
	v_pk_add_f32 v[102:103], v[102:103], v[238:239]
	v_pk_add_f32 v[100:101], v[100:101], v[236:237]
	global_store_dwordx4 v[118:119], v[100:103], off offset:128
	v_cvt_pk_bf16_f32 v104, v100, v101
	v_or_b32_e32 v106, 64, v124
	v_mov_b32_e32 v107, v125
	v_mul_f32_e32 v101, v101, v101
	v_fmac_f32_e32 v101, v100, v100
	v_lshl_add_u64 v[106:107], s[16:17], 0, v[106:107]
	v_fmac_f32_e32 v101, v102, v102
	v_cvt_pk_bf16_f32 v105, v102, v103
	flat_store_dwordx2 v[106:107], v[104:105]
	v_fmac_f32_e32 v101, v103, v103
	v_add_f32_e32 v104, v108, v101
	v_or_b32_e32 v124, 0x60, v124
	s_waitcnt vmcnt(6)
	v_pk_add_f32 v[98:99], v[98:99], v[242:243]
	v_pk_add_f32 v[96:97], v[96:97], v[240:241]
	global_store_dwordx4 v[118:119], v[96:99], off offset:192
	v_cvt_pk_bf16_f32 v100, v96, v97
	v_lshl_add_u64 v[102:103], s[16:17], 0, v[124:125]
	v_cvt_pk_bf16_f32 v101, v98, v99
	flat_store_dwordx2 v[102:103], v[100:101]
	v_mul_f32_e32 v97, v97, v97
	v_fmac_f32_e32 v97, v96, v96
	v_fmac_f32_e32 v97, v98, v98
	v_fmac_f32_e32 v97, v99, v99
	v_add_f32_e32 v96, v104, v97
	ds_bpermute_b32 v97, v120, v96
	s_waitcnt lgkmcnt(0)
	v_add_f32_e32 v96, v96, v97
	ds_bpermute_b32 v97, v121, v96
	s_and_saveexec_b64 s[2:3], vcc
	s_cbranch_execz .LBB0_251
	s_waitcnt lgkmcnt(0)
	v_add_f32_e32 v96, v96, v97
	flat_store_dword v[112:113], v96 offset:64
.LBB0_251:
	s_or_b64 exec, exec, s[2:3]
	v_or_b32_e32 v96, 32, v114
	s_waitcnt lgkmcnt(0)
	v_ashrrev_i32_e32 v97, 31, v96
	v_lshlrev_b64 v[96:97], 10, v[96:97]
	v_lshl_add_u64 v[102:103], v[116:117], 0, v[96:97]
	v_lshl_add_u64 v[96:97], v[102:103], 2, s[90:91]
	global_load_dwordx4 v[228:231], v[96:97], off
	global_load_dwordx4 v[232:235], v[96:97], off offset:64
	global_load_dwordx4 v[236:239], v[96:97], off offset:128
	global_load_dwordx4 v[240:243], v[96:97], off offset:192
	s_waitcnt vmcnt(3)
	v_pk_add_f32 v[94:95], v[94:95], v[230:231]
	v_lshlrev_b64 v[100:101], 1, v[102:103]
	v_pk_add_f32 v[92:93], v[92:93], v[228:229]
	v_lshl_add_u64 v[102:103], s[16:17], 0, v[100:101]
	v_cvt_pk_bf16_f32 v98, v92, v93
	global_store_dwordx4 v[96:97], v[92:95], off
	v_cvt_pk_bf16_f32 v99, v94, v95
	flat_store_dwordx2 v[102:103], v[98:99]
	v_mul_f32_e32 v98, v93, v93
	v_fmac_f32_e32 v98, v92, v92
	v_fmac_f32_e32 v98, v94, v94
	v_fmac_f32_e32 v98, v95, v95
	s_waitcnt vmcnt(4)
	v_pk_add_f32 v[90:91], v[90:91], v[234:235]
	v_pk_add_f32 v[88:89], v[88:89], v[232:233]
	global_store_dwordx4 v[96:97], v[88:91], off offset:64
	v_cvt_pk_bf16_f32 v92, v88, v89
	v_or_b32_e32 v94, 32, v100
	v_mov_b32_e32 v95, v101
	v_mul_f32_e32 v89, v89, v89
	v_fmac_f32_e32 v89, v88, v88
	v_lshl_add_u64 v[94:95], s[16:17], 0, v[94:95]
	v_fmac_f32_e32 v89, v90, v90
	v_cvt_pk_bf16_f32 v93, v90, v91
	flat_store_dwordx2 v[94:95], v[92:93]
	v_fmac_f32_e32 v89, v91, v91
	v_add_f32_e32 v92, v98, v89
	s_waitcnt vmcnt(5)
	v_pk_add_f32 v[86:87], v[86:87], v[238:239]
	v_pk_add_f32 v[84:85], v[84:85], v[236:237]
	global_store_dwordx4 v[96:97], v[84:87], off offset:128
	v_cvt_pk_bf16_f32 v88, v84, v85
	v_or_b32_e32 v90, 64, v100
	v_mov_b32_e32 v91, v101
	v_mul_f32_e32 v85, v85, v85
	v_fmac_f32_e32 v85, v84, v84
	v_lshl_add_u64 v[90:91], s[16:17], 0, v[90:91]
	v_fmac_f32_e32 v85, v86, v86
	v_cvt_pk_bf16_f32 v89, v86, v87
	flat_store_dwordx2 v[90:91], v[88:89]
	v_fmac_f32_e32 v85, v87, v87
	v_add_f32_e32 v88, v92, v85
	v_or_b32_e32 v100, 0x60, v100
	s_waitcnt vmcnt(6)
	v_pk_add_f32 v[82:83], v[82:83], v[242:243]
	v_pk_add_f32 v[80:81], v[80:81], v[240:241]
	global_store_dwordx4 v[96:97], v[80:83], off offset:192
	v_cvt_pk_bf16_f32 v84, v80, v81
	v_lshl_add_u64 v[86:87], s[16:17], 0, v[100:101]
	v_cvt_pk_bf16_f32 v85, v82, v83
	flat_store_dwordx2 v[86:87], v[84:85]
	v_mul_f32_e32 v81, v81, v81
	v_fmac_f32_e32 v81, v80, v80
	v_fmac_f32_e32 v81, v82, v82
	v_fmac_f32_e32 v81, v83, v83
	v_add_f32_e32 v80, v88, v81
	ds_bpermute_b32 v81, v120, v80
	s_waitcnt lgkmcnt(0)
	v_add_f32_e32 v80, v80, v81
	ds_bpermute_b32 v81, v121, v80
	s_and_saveexec_b64 s[2:3], vcc
	s_cbranch_execz .LBB0_253
	s_waitcnt lgkmcnt(0)
	v_add_f32_e32 v80, v80, v81
	flat_store_dword v[112:113], v80 offset:128
.LBB0_253:
	s_or_b64 exec, exec, s[2:3]
	v_or_b32_e32 v80, 48, v114
	s_waitcnt lgkmcnt(0)
	v_ashrrev_i32_e32 v81, 31, v80
	v_lshlrev_b64 v[80:81], 10, v[80:81]
	v_lshl_add_u64 v[86:87], v[116:117], 0, v[80:81]
	v_lshl_add_u64 v[80:81], v[86:87], 2, s[90:91]
	global_load_dwordx4 v[228:231], v[80:81], off
	global_load_dwordx4 v[232:235], v[80:81], off offset:64
	global_load_dwordx4 v[236:239], v[80:81], off offset:128
	global_load_dwordx4 v[240:243], v[80:81], off offset:192
	s_waitcnt vmcnt(3)
	v_pk_add_f32 v[78:79], v[78:79], v[230:231]
	v_lshlrev_b64 v[84:85], 1, v[86:87]
	v_pk_add_f32 v[76:77], v[76:77], v[228:229]
	v_lshl_add_u64 v[86:87], s[16:17], 0, v[84:85]
	v_cvt_pk_bf16_f32 v82, v76, v77
	global_store_dwordx4 v[80:81], v[76:79], off
	v_cvt_pk_bf16_f32 v83, v78, v79
	flat_store_dwordx2 v[86:87], v[82:83]
	v_mul_f32_e32 v82, v77, v77
	v_fmac_f32_e32 v82, v76, v76
	v_fmac_f32_e32 v82, v78, v78
	v_fmac_f32_e32 v82, v79, v79
	s_waitcnt vmcnt(4)
	v_pk_add_f32 v[74:75], v[74:75], v[234:235]
	v_pk_add_f32 v[72:73], v[72:73], v[232:233]
	global_store_dwordx4 v[80:81], v[72:75], off offset:64
	v_cvt_pk_bf16_f32 v76, v72, v73
	v_or_b32_e32 v78, 32, v84
	v_mov_b32_e32 v79, v85
	v_mul_f32_e32 v73, v73, v73
	v_fmac_f32_e32 v73, v72, v72
	v_lshl_add_u64 v[78:79], s[16:17], 0, v[78:79]
	v_fmac_f32_e32 v73, v74, v74
	v_cvt_pk_bf16_f32 v77, v74, v75
	flat_store_dwordx2 v[78:79], v[76:77]
	v_fmac_f32_e32 v73, v75, v75
	v_add_f32_e32 v76, v82, v73
	s_waitcnt vmcnt(5)
	v_pk_add_f32 v[70:71], v[70:71], v[238:239]
	v_pk_add_f32 v[68:69], v[68:69], v[236:237]
	global_store_dwordx4 v[80:81], v[68:71], off offset:128
	v_cvt_pk_bf16_f32 v72, v68, v69
	v_or_b32_e32 v74, 64, v84
	v_mov_b32_e32 v75, v85
	v_mul_f32_e32 v69, v69, v69
	v_fmac_f32_e32 v69, v68, v68
	v_lshl_add_u64 v[74:75], s[16:17], 0, v[74:75]
	v_fmac_f32_e32 v69, v70, v70
	v_cvt_pk_bf16_f32 v73, v70, v71
	flat_store_dwordx2 v[74:75], v[72:73]
	v_fmac_f32_e32 v69, v71, v71
	v_add_f32_e32 v72, v76, v69
	v_or_b32_e32 v84, 0x60, v84
	s_waitcnt vmcnt(6)
	v_pk_add_f32 v[66:67], v[66:67], v[242:243]
	v_pk_add_f32 v[64:65], v[64:65], v[240:241]
	global_store_dwordx4 v[80:81], v[64:67], off offset:192
	v_cvt_pk_bf16_f32 v68, v64, v65
	v_lshl_add_u64 v[70:71], s[16:17], 0, v[84:85]
	v_cvt_pk_bf16_f32 v69, v66, v67
	flat_store_dwordx2 v[70:71], v[68:69]
	v_mul_f32_e32 v65, v65, v65
	v_fmac_f32_e32 v65, v64, v64
	v_fmac_f32_e32 v65, v66, v66
	v_fmac_f32_e32 v65, v67, v67
	v_add_f32_e32 v64, v72, v65
	ds_bpermute_b32 v65, v120, v64
	s_waitcnt lgkmcnt(0)
	v_add_f32_e32 v64, v64, v65
	ds_bpermute_b32 v65, v121, v64
	s_and_saveexec_b64 s[2:3], vcc
	s_cbranch_execz .LBB0_255
	s_waitcnt lgkmcnt(0)
	v_add_f32_e32 v64, v64, v65
	flat_store_dword v[112:113], v64 offset:192
.LBB0_255:
	s_or_b64 exec, exec, s[2:3]
	v_or_b32_e32 v64, 64, v114
	s_waitcnt lgkmcnt(0)
	v_ashrrev_i32_e32 v65, 31, v64
	v_lshlrev_b64 v[64:65], 10, v[64:65]
	v_lshl_add_u64 v[70:71], v[116:117], 0, v[64:65]
	v_lshl_add_u64 v[64:65], v[70:71], 2, s[90:91]
	global_load_dwordx4 v[228:231], v[64:65], off
	global_load_dwordx4 v[232:235], v[64:65], off offset:64
	global_load_dwordx4 v[236:239], v[64:65], off offset:128
	global_load_dwordx4 v[240:243], v[64:65], off offset:192
	s_waitcnt vmcnt(3)
	v_pk_add_f32 v[62:63], v[62:63], v[230:231]
	v_lshlrev_b64 v[68:69], 1, v[70:71]
	v_pk_add_f32 v[60:61], v[60:61], v[228:229]
	v_lshl_add_u64 v[70:71], s[16:17], 0, v[68:69]
	v_cvt_pk_bf16_f32 v66, v60, v61
	global_store_dwordx4 v[64:65], v[60:63], off
	v_cvt_pk_bf16_f32 v67, v62, v63
	flat_store_dwordx2 v[70:71], v[66:67]
	v_mul_f32_e32 v66, v61, v61
	v_fmac_f32_e32 v66, v60, v60
	v_fmac_f32_e32 v66, v62, v62
	v_fmac_f32_e32 v66, v63, v63
	s_waitcnt vmcnt(4)
	v_pk_add_f32 v[58:59], v[58:59], v[234:235]
	v_pk_add_f32 v[56:57], v[56:57], v[232:233]
	global_store_dwordx4 v[64:65], v[56:59], off offset:64
	v_cvt_pk_bf16_f32 v60, v56, v57
	v_or_b32_e32 v62, 32, v68
	v_mov_b32_e32 v63, v69
	v_mul_f32_e32 v57, v57, v57
	v_fmac_f32_e32 v57, v56, v56
	v_lshl_add_u64 v[62:63], s[16:17], 0, v[62:63]
	v_fmac_f32_e32 v57, v58, v58
	v_cvt_pk_bf16_f32 v61, v58, v59
	flat_store_dwordx2 v[62:63], v[60:61]
	v_fmac_f32_e32 v57, v59, v59
	v_add_f32_e32 v60, v66, v57
	s_waitcnt vmcnt(5)
	v_pk_add_f32 v[54:55], v[54:55], v[238:239]
	v_pk_add_f32 v[52:53], v[52:53], v[236:237]
	global_store_dwordx4 v[64:65], v[52:55], off offset:128
	v_cvt_pk_bf16_f32 v56, v52, v53
	v_or_b32_e32 v58, 64, v68
	v_mov_b32_e32 v59, v69
	v_mul_f32_e32 v53, v53, v53
	v_fmac_f32_e32 v53, v52, v52
	v_lshl_add_u64 v[58:59], s[16:17], 0, v[58:59]
	v_fmac_f32_e32 v53, v54, v54
	v_cvt_pk_bf16_f32 v57, v54, v55
	flat_store_dwordx2 v[58:59], v[56:57]
	v_fmac_f32_e32 v53, v55, v55
	v_add_f32_e32 v56, v60, v53
	v_or_b32_e32 v68, 0x60, v68
	s_waitcnt vmcnt(6)
	v_pk_add_f32 v[50:51], v[50:51], v[242:243]
	v_pk_add_f32 v[48:49], v[48:49], v[240:241]
	global_store_dwordx4 v[64:65], v[48:51], off offset:192
	v_cvt_pk_bf16_f32 v52, v48, v49
	v_lshl_add_u64 v[54:55], s[16:17], 0, v[68:69]
	v_cvt_pk_bf16_f32 v53, v50, v51
	flat_store_dwordx2 v[54:55], v[52:53]
	v_mul_f32_e32 v49, v49, v49
	v_fmac_f32_e32 v49, v48, v48
	v_fmac_f32_e32 v49, v50, v50
	v_fmac_f32_e32 v49, v51, v51
	v_add_f32_e32 v48, v56, v49
	ds_bpermute_b32 v49, v120, v48
	s_waitcnt lgkmcnt(0)
	v_add_f32_e32 v48, v48, v49
	ds_bpermute_b32 v49, v121, v48
	s_and_saveexec_b64 s[2:3], vcc
	s_cbranch_execz .LBB0_257
	s_waitcnt lgkmcnt(0)
	v_add_f32_e32 v48, v48, v49
	flat_store_dword v[112:113], v48 offset:256
.LBB0_257:
	s_or_b64 exec, exec, s[2:3]
	v_or_b32_e32 v48, 0x50, v114
	s_waitcnt lgkmcnt(0)
	v_ashrrev_i32_e32 v49, 31, v48
	v_lshlrev_b64 v[48:49], 10, v[48:49]
	v_lshl_add_u64 v[54:55], v[116:117], 0, v[48:49]
	v_lshl_add_u64 v[48:49], v[54:55], 2, s[90:91]
	global_load_dwordx4 v[228:231], v[48:49], off
	global_load_dwordx4 v[232:235], v[48:49], off offset:64
	global_load_dwordx4 v[236:239], v[48:49], off offset:128
	global_load_dwordx4 v[240:243], v[48:49], off offset:192
	s_waitcnt vmcnt(3)
	v_pk_add_f32 v[46:47], v[46:47], v[230:231]
	v_lshlrev_b64 v[52:53], 1, v[54:55]
	v_pk_add_f32 v[44:45], v[44:45], v[228:229]
	v_lshl_add_u64 v[54:55], s[16:17], 0, v[52:53]
	v_cvt_pk_bf16_f32 v50, v44, v45
	global_store_dwordx4 v[48:49], v[44:47], off
	v_cvt_pk_bf16_f32 v51, v46, v47
	flat_store_dwordx2 v[54:55], v[50:51]
	v_mul_f32_e32 v50, v45, v45
	v_fmac_f32_e32 v50, v44, v44
	v_fmac_f32_e32 v50, v46, v46
	v_fmac_f32_e32 v50, v47, v47
	s_waitcnt vmcnt(4)
	v_pk_add_f32 v[42:43], v[42:43], v[234:235]
	v_pk_add_f32 v[40:41], v[40:41], v[232:233]
	global_store_dwordx4 v[48:49], v[40:43], off offset:64
	v_cvt_pk_bf16_f32 v44, v40, v41
	v_or_b32_e32 v46, 32, v52
	v_mov_b32_e32 v47, v53
	v_mul_f32_e32 v41, v41, v41
	v_fmac_f32_e32 v41, v40, v40
	v_lshl_add_u64 v[46:47], s[16:17], 0, v[46:47]
	v_fmac_f32_e32 v41, v42, v42
	v_cvt_pk_bf16_f32 v45, v42, v43
	flat_store_dwordx2 v[46:47], v[44:45]
	v_fmac_f32_e32 v41, v43, v43
	v_add_f32_e32 v44, v50, v41
	s_waitcnt vmcnt(5)
	v_pk_add_f32 v[38:39], v[38:39], v[238:239]
	v_pk_add_f32 v[36:37], v[36:37], v[236:237]
	global_store_dwordx4 v[48:49], v[36:39], off offset:128
	v_cvt_pk_bf16_f32 v40, v36, v37
	v_or_b32_e32 v42, 64, v52
	v_mov_b32_e32 v43, v53
	v_mul_f32_e32 v37, v37, v37
	v_fmac_f32_e32 v37, v36, v36
	v_lshl_add_u64 v[42:43], s[16:17], 0, v[42:43]
	v_fmac_f32_e32 v37, v38, v38
	v_cvt_pk_bf16_f32 v41, v38, v39
	flat_store_dwordx2 v[42:43], v[40:41]
	v_fmac_f32_e32 v37, v39, v39
	v_add_f32_e32 v40, v44, v37
	v_or_b32_e32 v52, 0x60, v52
	s_waitcnt vmcnt(6)
	v_pk_add_f32 v[34:35], v[34:35], v[242:243]
	v_pk_add_f32 v[32:33], v[32:33], v[240:241]
	global_store_dwordx4 v[48:49], v[32:35], off offset:192
	v_cvt_pk_bf16_f32 v36, v32, v33
	v_lshl_add_u64 v[38:39], s[16:17], 0, v[52:53]
	v_cvt_pk_bf16_f32 v37, v34, v35
	flat_store_dwordx2 v[38:39], v[36:37]
	v_mul_f32_e32 v33, v33, v33
	v_fmac_f32_e32 v33, v32, v32
	v_fmac_f32_e32 v33, v34, v34
	v_fmac_f32_e32 v33, v35, v35
	v_add_f32_e32 v32, v40, v33
	ds_bpermute_b32 v33, v120, v32
	s_waitcnt lgkmcnt(0)
	v_add_f32_e32 v32, v32, v33
	ds_bpermute_b32 v33, v121, v32
	s_and_saveexec_b64 s[2:3], vcc
	s_cbranch_execz .LBB0_259
	s_waitcnt lgkmcnt(0)
	v_add_f32_e32 v32, v32, v33
	flat_store_dword v[112:113], v32 offset:320
.LBB0_259:
	s_or_b64 exec, exec, s[2:3]
	v_or_b32_e32 v32, 0x60, v114
	s_waitcnt lgkmcnt(0)
	v_ashrrev_i32_e32 v33, 31, v32
	v_lshlrev_b64 v[32:33], 10, v[32:33]
	v_lshl_add_u64 v[38:39], v[116:117], 0, v[32:33]
	v_lshl_add_u64 v[32:33], v[38:39], 2, s[90:91]
	global_load_dwordx4 v[228:231], v[32:33], off
	global_load_dwordx4 v[232:235], v[32:33], off offset:64
	global_load_dwordx4 v[236:239], v[32:33], off offset:128
	global_load_dwordx4 v[240:243], v[32:33], off offset:192
	s_waitcnt vmcnt(3)
	v_pk_add_f32 v[30:31], v[30:31], v[230:231]
	v_lshlrev_b64 v[36:37], 1, v[38:39]
	v_pk_add_f32 v[28:29], v[28:29], v[228:229]
	v_lshl_add_u64 v[38:39], s[16:17], 0, v[36:37]
	v_cvt_pk_bf16_f32 v34, v28, v29
	global_store_dwordx4 v[32:33], v[28:31], off
	v_cvt_pk_bf16_f32 v35, v30, v31
	flat_store_dwordx2 v[38:39], v[34:35]
	v_mul_f32_e32 v34, v29, v29
	v_fmac_f32_e32 v34, v28, v28
	v_fmac_f32_e32 v34, v30, v30
	v_fmac_f32_e32 v34, v31, v31
	s_waitcnt vmcnt(4)
	v_pk_add_f32 v[26:27], v[26:27], v[234:235]
	v_pk_add_f32 v[24:25], v[24:25], v[232:233]
	global_store_dwordx4 v[32:33], v[24:27], off offset:64
	v_cvt_pk_bf16_f32 v28, v24, v25
	v_or_b32_e32 v30, 32, v36
	v_mov_b32_e32 v31, v37
	v_mul_f32_e32 v25, v25, v25
	v_fmac_f32_e32 v25, v24, v24
	v_lshl_add_u64 v[30:31], s[16:17], 0, v[30:31]
	v_fmac_f32_e32 v25, v26, v26
	v_cvt_pk_bf16_f32 v29, v26, v27
	flat_store_dwordx2 v[30:31], v[28:29]
	v_fmac_f32_e32 v25, v27, v27
	v_add_f32_e32 v28, v34, v25
	s_waitcnt vmcnt(5)
	v_pk_add_f32 v[22:23], v[22:23], v[238:239]
	v_pk_add_f32 v[20:21], v[20:21], v[236:237]
	global_store_dwordx4 v[32:33], v[20:23], off offset:128
	v_cvt_pk_bf16_f32 v24, v20, v21
	v_or_b32_e32 v26, 64, v36
	v_mov_b32_e32 v27, v37
	v_mul_f32_e32 v21, v21, v21
	v_fmac_f32_e32 v21, v20, v20
	v_lshl_add_u64 v[26:27], s[16:17], 0, v[26:27]
	v_fmac_f32_e32 v21, v22, v22
	v_cvt_pk_bf16_f32 v25, v22, v23
	flat_store_dwordx2 v[26:27], v[24:25]
	v_fmac_f32_e32 v21, v23, v23
	v_add_f32_e32 v24, v28, v21
	v_or_b32_e32 v36, 0x60, v36
	s_waitcnt vmcnt(6)
	v_pk_add_f32 v[18:19], v[18:19], v[242:243]
	v_pk_add_f32 v[16:17], v[16:17], v[240:241]
	global_store_dwordx4 v[32:33], v[16:19], off offset:192
	v_cvt_pk_bf16_f32 v20, v16, v17
	v_lshl_add_u64 v[22:23], s[16:17], 0, v[36:37]
	v_cvt_pk_bf16_f32 v21, v18, v19
	flat_store_dwordx2 v[22:23], v[20:21]
	v_mul_f32_e32 v17, v17, v17
	v_fmac_f32_e32 v17, v16, v16
	v_fmac_f32_e32 v17, v18, v18
	v_fmac_f32_e32 v17, v19, v19
	v_add_f32_e32 v16, v24, v17
	ds_bpermute_b32 v17, v120, v16
	s_waitcnt lgkmcnt(0)
	v_add_f32_e32 v16, v16, v17
	ds_bpermute_b32 v17, v121, v16
	s_and_saveexec_b64 s[2:3], vcc
	s_cbranch_execz .LBB0_261
	s_waitcnt lgkmcnt(0)
	v_add_f32_e32 v16, v16, v17
	flat_store_dword v[112:113], v16 offset:384
.LBB0_261:
	s_or_b64 exec, exec, s[2:3]
	v_or_b32_e32 v16, 0x70, v114
	s_waitcnt lgkmcnt(0)
	v_ashrrev_i32_e32 v17, 31, v16
	v_lshlrev_b64 v[16:17], 10, v[16:17]
	v_lshl_add_u64 v[22:23], v[116:117], 0, v[16:17]
	v_lshl_add_u64 v[16:17], v[22:23], 2, s[90:91]
	global_load_dwordx4 v[228:231], v[16:17], off
	global_load_dwordx4 v[232:235], v[16:17], off offset:64
	global_load_dwordx4 v[236:239], v[16:17], off offset:128
	global_load_dwordx4 v[240:243], v[16:17], off offset:192
	s_waitcnt vmcnt(3)
	v_pk_add_f32 v[14:15], v[14:15], v[230:231]
	v_lshlrev_b64 v[20:21], 1, v[22:23]
	v_pk_add_f32 v[12:13], v[12:13], v[228:229]
	v_lshl_add_u64 v[22:23], s[16:17], 0, v[20:21]
	v_cvt_pk_bf16_f32 v18, v12, v13
	global_store_dwordx4 v[16:17], v[12:15], off
	v_cvt_pk_bf16_f32 v19, v14, v15
	flat_store_dwordx2 v[22:23], v[18:19]
	v_mul_f32_e32 v18, v13, v13
	v_fmac_f32_e32 v18, v12, v12
	v_fmac_f32_e32 v18, v14, v14
	v_fmac_f32_e32 v18, v15, v15
	s_waitcnt vmcnt(4)
	v_pk_add_f32 v[10:11], v[10:11], v[234:235]
	v_pk_add_f32 v[8:9], v[8:9], v[232:233]
	global_store_dwordx4 v[16:17], v[8:11], off offset:64
	v_cvt_pk_bf16_f32 v12, v8, v9
	v_or_b32_e32 v14, 32, v20
	v_mov_b32_e32 v15, v21
	v_mul_f32_e32 v9, v9, v9
	v_fmac_f32_e32 v9, v8, v8
	v_lshl_add_u64 v[14:15], s[16:17], 0, v[14:15]
	v_fmac_f32_e32 v9, v10, v10
	v_cvt_pk_bf16_f32 v13, v10, v11
	flat_store_dwordx2 v[14:15], v[12:13]
	v_fmac_f32_e32 v9, v11, v11
	v_add_f32_e32 v12, v18, v9
	s_waitcnt vmcnt(5)
	v_pk_add_f32 v[6:7], v[6:7], v[238:239]
	v_pk_add_f32 v[4:5], v[4:5], v[236:237]
	global_store_dwordx4 v[16:17], v[4:7], off offset:128
	v_cvt_pk_bf16_f32 v8, v4, v5
	v_or_b32_e32 v10, 64, v20
	v_mov_b32_e32 v11, v21
	v_mul_f32_e32 v5, v5, v5
	v_fmac_f32_e32 v5, v4, v4
	v_lshl_add_u64 v[10:11], s[16:17], 0, v[10:11]
	v_fmac_f32_e32 v5, v6, v6
	v_cvt_pk_bf16_f32 v9, v6, v7
	flat_store_dwordx2 v[10:11], v[8:9]
	v_fmac_f32_e32 v5, v7, v7
	v_add_f32_e32 v8, v12, v5
	v_or_b32_e32 v20, 0x60, v20
	s_waitcnt vmcnt(6)
	v_pk_add_f32 v[2:3], v[2:3], v[242:243]
	v_pk_add_f32 v[0:1], v[0:1], v[240:241]
	global_store_dwordx4 v[16:17], v[0:3], off offset:192
	v_cvt_pk_bf16_f32 v4, v0, v1
	v_lshl_add_u64 v[6:7], s[16:17], 0, v[20:21]
	v_cvt_pk_bf16_f32 v5, v2, v3
	flat_store_dwordx2 v[6:7], v[4:5]
	v_mul_f32_e32 v1, v1, v1
	v_fmac_f32_e32 v1, v0, v0
	v_fmac_f32_e32 v1, v2, v2
	v_fmac_f32_e32 v1, v3, v3
	v_add_f32_e32 v0, v8, v1
	ds_bpermute_b32 v1, v120, v0
	s_waitcnt lgkmcnt(0)
	v_add_f32_e32 v0, v0, v1
	ds_bpermute_b32 v1, v121, v0
	s_and_saveexec_b64 s[2:3], vcc
	s_cbranch_execz .LBB0_244
	s_waitcnt lgkmcnt(0)
	v_add_f32_e32 v0, v0, v1
	flat_store_dword v[112:113], v0 offset:448
	s_branch .LBB0_244
